# MoBA gate: block-mean key loads issued up front (6 of 8 k-steps) instead of one load-wait-MFMA round trip per k-step
# speedup vs baseline: 1.0101x; 1.0003x over previous
; __device__ __forceinline__ bf16_t cvt_bf16(float v) { return (bf16_t)(cvt_pk_bf16(v, 0.f) & 0xffffu); }
; template <int DQ, int TYPE>
; __device__ __forceinline__ void attn_item(PP p, int layer, int b, int h, int qt, char* lds, const int tid_, unsigned* next_ctr, volatile XLAS unsigned* slot) {
;     ...
;     A_GLOAD(A, j_lo);
;     bf16x8 qf[NKS];
;     {
;         const bf16_t* qrow = Qp + (size_t)qpos * ldq + 8 * hh;
; #pragma unroll
;         for (int ks = 0; ks < NKS; ++ks) qf[ks] = *(const bf16x8*)(qrow + 16 * ks);
;         if (TYPE == 0) {
;             const float* r64 = (const float*)(p->ws + OFF_R64) + (size_t)qpos * 64;
; #pragma unroll
;             for (int kk = 0; kk < 2; ++kk) {
;                 bf16x8 x1 = qf[8 + kk], x2 = qf[10 + kk], o1, o2;
; #pragma unroll
;                 for (int j = 0; j < 8; ++j) {
;                     const int f = 16 * kk + 8 * hh + j;
;                     const float cs = r64[2 * f], sn = r64[2 * f + 1];
;                     const float a = __uint_as_float(((unsigned)(unsigned short)x1[j]) << 16), bb = __uint_as_float(((unsigned)(unsigned short)x2[j]) << 16);
;                     o1[j] = (short)cvt_bf16(a * cs - bb * sn); o2[j] = (short)cvt_bf16(bb * cs + a * sn);
;                 }
;                 qf[8 + kk] = o1; qf[10 + kk] = o2;
;             }
;         }
;     }
;     unsigned qmask = 0;
;     if (TYPE == 1) {
;         if (own > 0) {
;             const float* kb = (const float*)(p->ws + OFF_KBARF) + (size_t)layer * 16384 + (size_t)(b * 4 + h) * 16 * 128;
;             f32x16 g = {};
; #pragma unroll
;             for (int ks = 0; ks < 8; ++ks) {
;                 bf16x8 a = {};
;                 if (r < 16) {
;                     const f32x4 k0v = *(const f32x4*)(kb + r * 128 + 16 * ks + 8 * hh), k1v = *(const f32x4*)(kb + r * 128 + 16 * ks + 8 * hh + 4);
;                     u32x4 pk; pk.x = cvt_pk_bf16(k0v[0] * (1.0f / 256.0f), k0v[1] * (1.0f / 256.0f)); pk.y = cvt_pk_bf16(k0v[2] * (1.0f / 256.0f), k0v[3] * (1.0f / 256.0f));
;                     pk.z = cvt_pk_bf16(k1v[0] * (1.0f / 256.0f), k1v[1] * (1.0f / 256.0f)); pk.w = cvt_pk_bf16(k1v[2] * (1.0f / 256.0f), k1v[3] * (1.0f / 256.0f));
;                     a = __builtin_bit_cast(bf16x8, pk);
;                 }
;                 g = __builtin_amdgcn_mfma_f32_32x32x16_bf16(a, qf[ks], g, 0, 0, 0);
;             }
.LBB0_423:
	s_and_b64 vcc, exec, s[8:9]
	s_cbranch_vccz .LBB0_385
	s_ashr_i32 s49, s54, 1
	s_sub_i32 s80, 31, s49
	s_bitcmp1_b32 s54, 0
	s_cselect_b64 s[12:13], -1, 0
	v_lshlrev_b32_e32 v156, 3, v181
	v_ashrrev_i32_e32 v166, 4, v181
	v_add_u32_e32 v0, 0x200, v181
	v_bfe_u32 v155, v181, 5, 1
	s_mov_b64 s[8:9], -1
	s_and_b64 vcc, exec, s[12:13]
	v_and_b32_e32 v154, 31, v181
	v_and_b32_e32 v183, 63, v181
	v_and_b32_e32 v185, 0x78, v156
	v_ashrrev_i32_e32 v167, 31, v166
	v_ashrrev_i32_e32 v168, 4, v0
	v_lshlrev_b32_e32 v170, 1, v166
	v_lshlrev_b32_e32 v153, 3, v155
	v_lshlrev_b32_e32 v146, 4, v155
	s_cbranch_vccz .LBB0_658
	s_lshr_b32 s96, s47, 2
	v_readfirstlane_b32 s88, v181
	s_and_b32 s97, s48, 3
	s_bfe_u32 s81, s88, 0x20006
	s_lshl_b32 s12, s96, 22
	s_add_u32 s8, s23, s12
	s_addc_u32 s9, s24, 0
	s_lshl_b32 s13, s97, 8
	s_add_u32 s8, s8, s13
	s_addc_u32 s9, s9, 0
	s_add_u32 s14, s25, s12
	s_addc_u32 s15, s26, 0
	s_lshl_b32 s16, s80, 7
	s_lshl_b32 s17, s81, 5
	s_or_b32 s95, s17, s16
	s_add_u32 s12, s27, s12
	v_lshlrev_b32_e32 v0, 1, v185
	s_addc_u32 s16, s29, 0
	v_lshl_add_u64 v[148:149], s[8:9], 0, v[0:1]
	v_lshlrev_b64 v[2:3], 10, v[166:167]
	v_ashrrev_i32_e32 v169, 31, v168
	s_add_u32 s8, s14, s13
	v_lshl_add_u64 v[2:3], v[148:149], 0, v[2:3]
	v_lshlrev_b64 v[4:5], 10, v[168:169]
	s_addc_u32 s9, s15, 0
	v_ashrrev_i32_e32 v171, 31, v170
	v_lshl_add_u64 v[4:5], v[148:149], 0, v[4:5]
	global_load_dwordx4 v[82:85], v[2:3], off
	global_load_dwordx4 v[86:89], v[4:5], off
	s_lshr_b32 s94, s80, 1
	v_lshl_add_u64 v[150:151], s[8:9], 0, v[0:1]
	v_lshlrev_b64 v[2:3], 10, v[170:171]
	v_lshl_add_u64 v[2:3], v[150:151], 0, v[2:3]
	s_add_u32 s8, s12, s13
	v_or_b32_e32 v0, s95, v154
	global_load_dwordx4 v[106:109], v[2:3], off
	global_load_dwordx4 v[118:121], v[2:3], off offset:1024
	s_addc_u32 s9, s16, 0
	v_lshlrev_b64 v[2:3], 10, v[0:1]
	v_lshl_add_u64 v[2:3], s[8:9], 0, v[2:3]
	v_mov_b32_e32 v147, v1
	v_lshl_add_u64 v[2:3], v[2:3], 0, v[146:147]
	global_load_dwordx4 v[90:93], v[2:3], off
	global_load_dwordx4 v[94:97], v[2:3], off offset:32
	global_load_dwordx4 v[98:101], v[2:3], off offset:64
	global_load_dwordx4 v[102:105], v[2:3], off offset:96
	global_load_dwordx4 v[110:113], v[2:3], off offset:128
	global_load_dwordx4 v[114:117], v[2:3], off offset:160
	global_load_dwordx4 v[122:125], v[2:3], off offset:192
	global_load_dwordx4 v[126:129], v[2:3], off offset:224
	s_cmp_lt_u32 s80, 2
	v_mov_b32_e32 v157, 0
	s_cbranch_scc1 .LBB0_635
	s_lshl_b32 s8, s97, 13
	s_lshl_b32 s9, s96, 15
	s_or_b32 s8, s9, s8
	s_add_u32 s8, s30, s8
	s_addc_u32 s9, s31, 0
	v_lshlrev_b32_e32 v2, 9, v154
	v_mov_b32_e32 v3, v1
	v_lshl_add_u64 v[2:3], s[8:9], 0, v[2:3]
	v_lshlrev_b32_e32 v4, 2, v153
	v_mov_b32_e32 v5, v1
	v_cmp_gt_u32_e32 vcc, 16, v154
	v_lshl_add_u64 v[24:25], v[2:3], 0, v[4:5]
	v_mov_b32_e32 v18, 0
	v_mov_b32_e32 v19, 0
	v_mov_b32_e32 v20, 0
	v_mov_b32_e32 v21, 0
	v_mov_b32_e32 v26, 0
	v_mov_b32_e32 v27, 0
	v_mov_b32_e32 v28, 0
	v_mov_b32_e32 v29, 0
	s_and_saveexec_b64 s[8:9], vcc
	s_cbranch_execz .Lgate_l0
	global_load_dwordx4 v[30:33], v[24:25], off
	global_load_dwordx4 v[34:37], v[24:25], off offset:16
	global_load_dwordx4 v[38:41], v[24:25], off offset:64
	global_load_dwordx4 v[42:45], v[24:25], off offset:80
	global_load_dwordx4 v[46:49], v[24:25], off offset:128
	global_load_dwordx4 v[50:53], v[24:25], off offset:144
	global_load_dwordx4 v[54:57], v[24:25], off offset:192
	global_load_dwordx4 v[58:61], v[24:25], off offset:208
	global_load_dwordx4 v[62:65], v[24:25], off offset:256
	global_load_dwordx4 v[66:69], v[24:25], off offset:272
	global_load_dwordx4 v[70:73], v[24:25], off offset:320
	global_load_dwordx4 v[74:77], v[24:25], off offset:336
.Lgate_l0:
	s_or_b64 exec, exec, s[8:9]
	s_and_saveexec_b64 s[8:9], vcc
	s_cbranch_execz .Lgate_c0
	s_waitcnt vmcnt(10)
	v_mul_f32_e32 v30, 0x3b800000, v30
	v_mul_f32_e32 v31, 0x3b800000, v31
	v_mul_f32_e32 v32, 0x3b800000, v32
	v_mul_f32_e32 v33, 0x3b800000, v33
	v_mul_f32_e32 v34, 0x3b800000, v34
	v_mul_f32_e32 v35, 0x3b800000, v35
	v_mul_f32_e32 v36, 0x3b800000, v36
	v_mul_f32_e32 v37, 0x3b800000, v37
	v_cvt_pk_bf16_f32 v18, v30, v31
	v_cvt_pk_bf16_f32 v19, v32, v33
	v_cvt_pk_bf16_f32 v20, v34, v35
	v_cvt_pk_bf16_f32 v21, v36, v37
	global_load_dwordx4 v[30:33], v[24:25], off offset:384
	global_load_dwordx4 v[34:37], v[24:25], off offset:400
.Lgate_c0:
	s_or_b64 exec, exec, s[8:9]
	s_nop 1
	v_mfma_f32_32x32x16_bf16 v[2:17], v[18:21], v[90:93], 0
	s_and_saveexec_b64 s[8:9], vcc
	s_cbranch_execz .Lgate_c1
	s_waitcnt vmcnt(10)
	v_mul_f32_e32 v38, 0x3b800000, v38
	v_mul_f32_e32 v39, 0x3b800000, v39
	v_mul_f32_e32 v40, 0x3b800000, v40
	v_mul_f32_e32 v41, 0x3b800000, v41
	v_mul_f32_e32 v42, 0x3b800000, v42
	v_mul_f32_e32 v43, 0x3b800000, v43
	v_mul_f32_e32 v44, 0x3b800000, v44
	v_mul_f32_e32 v45, 0x3b800000, v45
	v_cvt_pk_bf16_f32 v26, v38, v39
	v_cvt_pk_bf16_f32 v27, v40, v41
	v_cvt_pk_bf16_f32 v28, v42, v43
	v_cvt_pk_bf16_f32 v29, v44, v45
	global_load_dwordx4 v[38:41], v[24:25], off offset:448
	global_load_dwordx4 v[42:45], v[24:25], off offset:464
; __device__ __forceinline__ unsigned cvt_pk_bf16(float lo, float hi) { unsigned r; asm volatile("v_cvt_pk_bf16_f32 %0, %1, %2" : "=v"(r) : "v"(lo), "v"(hi)); return r; }
; template <int DQ, int TYPE>
; __device__ __forceinline__ void attn_item(PP p, int layer, int b, int h, int qt, char* lds, const int tid_, unsigned* next_ctr, volatile XLAS unsigned* slot) {
;     ...
;             f32x16 g = {};
; #pragma unroll
;             for (int ks = 0; ks < 8; ++ks) {
;                 bf16x8 a = {};
;                 if (r < 16) {
;                     const f32x4 k0v = *(const f32x4*)(kb + r * 128 + 16 * ks + 8 * hh), k1v = *(const f32x4*)(kb + r * 128 + 16 * ks + 8 * hh + 4);
;                     u32x4 pk; pk.x = cvt_pk_bf16(k0v[0] * (1.0f / 256.0f), k0v[1] * (1.0f / 256.0f)); pk.y = cvt_pk_bf16(k0v[2] * (1.0f / 256.0f), k0v[3] * (1.0f / 256.0f));
;                     pk.z = cvt_pk_bf16(k1v[0] * (1.0f / 256.0f), k1v[1] * (1.0f / 256.0f)); pk.w = cvt_pk_bf16(k1v[2] * (1.0f / 256.0f), k1v[3] * (1.0f / 256.0f));
;                     a = __builtin_bit_cast(bf16x8, pk);
;                 }
;                 g = __builtin_amdgcn_mfma_f32_32x32x16_bf16(a, qf[ks], g, 0, 0, 0);
;             }
;             float mine[8], theirs[8];
; #pragma unroll
;             for (int i = 0; i < 8; ++i) { mine[i] = g[i]; theirs[i] = __shfl_xor(g[i], 32); }
;             unsigned bits = 0;
; #pragma unroll
;             for (int i = 0; i < 8; ++i) {
;                 const int n = 8 * (i >> 2) + 4 * hh + (i & 3);
;                 int rank = 0;
; #pragma unroll
;                 for (int i2 = 0; i2 < 8; ++i2) {
;                     const int n1 = 8 * (i2 >> 2) + 4 * hh + (i2 & 3), n2 = 8 * (i2 >> 2) + 4 * (1 - hh) + (i2 & 3);
;                     if (n1 < own && (mine[i2] > mine[i] || (mine[i2] == mine[i] && n1 < n))) ++rank;
;                     if (n2 < own && (theirs[i2] > mine[i] || (theirs[i2] == mine[i] && n2 < n))) ++rank;
;                 }
;                 if (n < own && rank < 3) bits |= 1u << n;
;             }
;             qmask = bits | (unsigned)__shfl_xor((int)bits, 32);
.Lgate_c1:
	s_or_b64 exec, exec, s[8:9]
	s_nop 1
	v_mfma_f32_32x32x16_bf16 v[2:17], v[26:29], v[94:97], v[2:17]
	s_and_saveexec_b64 s[8:9], vcc
	s_cbranch_execz .Lgate_c2
	s_waitcnt vmcnt(10)
	v_mul_f32_e32 v46, 0x3b800000, v46
	v_mul_f32_e32 v47, 0x3b800000, v47
	v_mul_f32_e32 v48, 0x3b800000, v48
	v_mul_f32_e32 v49, 0x3b800000, v49
	v_mul_f32_e32 v50, 0x3b800000, v50
	v_mul_f32_e32 v51, 0x3b800000, v51
	v_mul_f32_e32 v52, 0x3b800000, v52
	v_mul_f32_e32 v53, 0x3b800000, v53
	v_cvt_pk_bf16_f32 v18, v46, v47
	v_cvt_pk_bf16_f32 v19, v48, v49
	v_cvt_pk_bf16_f32 v20, v50, v51
	v_cvt_pk_bf16_f32 v21, v52, v53
.Lgate_c2:
	s_or_b64 exec, exec, s[8:9]
	s_nop 1
	v_mfma_f32_32x32x16_bf16 v[2:17], v[18:21], v[98:101], v[2:17]
	s_and_saveexec_b64 s[8:9], vcc
	s_cbranch_execz .Lgate_c3
	s_waitcnt vmcnt(8)
	v_mul_f32_e32 v54, 0x3b800000, v54
	v_mul_f32_e32 v55, 0x3b800000, v55
	v_mul_f32_e32 v56, 0x3b800000, v56
	v_mul_f32_e32 v57, 0x3b800000, v57
	v_mul_f32_e32 v58, 0x3b800000, v58
	v_mul_f32_e32 v59, 0x3b800000, v59
	v_mul_f32_e32 v60, 0x3b800000, v60
	v_mul_f32_e32 v61, 0x3b800000, v61
	v_cvt_pk_bf16_f32 v26, v54, v55
	v_cvt_pk_bf16_f32 v27, v56, v57
	v_cvt_pk_bf16_f32 v28, v58, v59
	v_cvt_pk_bf16_f32 v29, v60, v61
.Lgate_c3:
	s_or_b64 exec, exec, s[8:9]
	s_nop 1
	v_mfma_f32_32x32x16_bf16 v[2:17], v[26:29], v[102:105], v[2:17]
	s_and_saveexec_b64 s[8:9], vcc
	s_cbranch_execz .Lgate_c4
	s_waitcnt vmcnt(6)
	v_mul_f32_e32 v62, 0x3b800000, v62
	v_mul_f32_e32 v63, 0x3b800000, v63
	v_mul_f32_e32 v64, 0x3b800000, v64
	v_mul_f32_e32 v65, 0x3b800000, v65
	v_mul_f32_e32 v66, 0x3b800000, v66
	v_mul_f32_e32 v67, 0x3b800000, v67
	v_mul_f32_e32 v68, 0x3b800000, v68
	v_mul_f32_e32 v69, 0x3b800000, v69
	v_cvt_pk_bf16_f32 v18, v62, v63
	v_cvt_pk_bf16_f32 v19, v64, v65
	v_cvt_pk_bf16_f32 v20, v66, v67
	v_cvt_pk_bf16_f32 v21, v68, v69
.Lgate_c4:
	s_or_b64 exec, exec, s[8:9]
	s_nop 1
	v_mfma_f32_32x32x16_bf16 v[2:17], v[18:21], v[110:113], v[2:17]
	s_and_saveexec_b64 s[8:9], vcc
	s_cbranch_execz .Lgate_c5
	s_waitcnt vmcnt(4)
	v_mul_f32_e32 v70, 0x3b800000, v70
	v_mul_f32_e32 v71, 0x3b800000, v71
	v_mul_f32_e32 v72, 0x3b800000, v72
	v_mul_f32_e32 v73, 0x3b800000, v73
	v_mul_f32_e32 v74, 0x3b800000, v74
	v_mul_f32_e32 v75, 0x3b800000, v75
	v_mul_f32_e32 v76, 0x3b800000, v76
	v_mul_f32_e32 v77, 0x3b800000, v77
	v_cvt_pk_bf16_f32 v26, v70, v71
	v_cvt_pk_bf16_f32 v27, v72, v73
	v_cvt_pk_bf16_f32 v28, v74, v75
	v_cvt_pk_bf16_f32 v29, v76, v77
.Lgate_c5:
	s_or_b64 exec, exec, s[8:9]
	s_nop 1
	v_mfma_f32_32x32x16_bf16 v[2:17], v[26:29], v[114:117], v[2:17]
	s_and_saveexec_b64 s[8:9], vcc
	s_cbranch_execz .Lgate_c6
	s_waitcnt vmcnt(2)
	v_mul_f32_e32 v30, 0x3b800000, v30
	v_mul_f32_e32 v31, 0x3b800000, v31
	v_mul_f32_e32 v32, 0x3b800000, v32
	v_mul_f32_e32 v33, 0x3b800000, v33
	v_mul_f32_e32 v34, 0x3b800000, v34
	v_mul_f32_e32 v35, 0x3b800000, v35
	v_mul_f32_e32 v36, 0x3b800000, v36
	v_mul_f32_e32 v37, 0x3b800000, v37
	v_cvt_pk_bf16_f32 v18, v30, v31
	v_cvt_pk_bf16_f32 v19, v32, v33
	v_cvt_pk_bf16_f32 v20, v34, v35
	v_cvt_pk_bf16_f32 v21, v36, v37
.Lgate_c6:
	s_or_b64 exec, exec, s[8:9]
	s_nop 1
	v_mfma_f32_32x32x16_bf16 v[2:17], v[18:21], v[122:125], v[2:17]
	s_and_saveexec_b64 s[8:9], vcc
	s_cbranch_execz .Lgate_c7
	s_waitcnt vmcnt(0)
	v_mul_f32_e32 v38, 0x3b800000, v38
	v_mul_f32_e32 v39, 0x3b800000, v39
	v_mul_f32_e32 v40, 0x3b800000, v40
	v_mul_f32_e32 v41, 0x3b800000, v41
	v_mul_f32_e32 v42, 0x3b800000, v42
	v_mul_f32_e32 v43, 0x3b800000, v43
	v_mul_f32_e32 v44, 0x3b800000, v44
	v_mul_f32_e32 v45, 0x3b800000, v45
	v_cvt_pk_bf16_f32 v26, v38, v39
	v_cvt_pk_bf16_f32 v27, v40, v41
	v_cvt_pk_bf16_f32 v28, v42, v43
	v_cvt_pk_bf16_f32 v29, v44, v45
.Lgate_c7:
	s_or_b64 exec, exec, s[8:9]
	s_nop 1
	v_mfma_f32_32x32x16_bf16 v[2:17], v[26:29], v[126:129], v[2:17]
	s_nop 11
	v_and_b32_e32 v11, 64, v224
	v_xor_b32_e32 v10, 32, v224
	v_add_u32_e32 v11, 64, v11
	v_cmp_lt_i32_e32 vcc, v10, v11
	v_lshlrev_b32_e32 v11, 2, v155
	v_xor_b32_e32 v23, 4, v11
	v_cndmask_b32_e32 v10, v224, v10, vcc
	v_lshlrev_b32_e32 v10, 2, v10
	ds_bpermute_b32 v20, v10, v2
	ds_bpermute_b32 v19, v10, v3
	ds_bpermute_b32 v18, v10, v4
	ds_bpermute_b32 v17, v10, v5
	ds_bpermute_b32 v15, v10, v6
	ds_bpermute_b32 v14, v10, v7
	ds_bpermute_b32 v13, v10, v8
	ds_bpermute_b32 v12, v10, v9
	v_mov_b32_e32 v16, 0
	v_cmp_gt_u32_e64 s[56:57], s94, v23
	s_and_saveexec_b64 s[8:9], s[56:57]
	s_cbranch_execz .LBB0_448
	s_waitcnt lgkmcnt(7)
	v_cmp_lt_f32_e64 s[12:13], v2, v20
	v_cmp_nlt_f32_e32 vcc, v2, v20
	s_and_saveexec_b64 s[14:15], vcc
	v_cmp_eq_f32_e32 vcc, v2, v20
	v_cmp_lt_u32_e64 s[50:51], v23, v11
	s_and_b64 s[16:17], vcc, s[50:51]
	s_andn2_b64 s[12:13], s[12:13], exec
	s_and_b64 s[16:17], s[16:17], exec
	s_or_b64 s[12:13], s[12:13], s[16:17]
	s_or_b64 exec, exec, s[14:15]
	v_mov_b32_e32 v16, 0
	s_and_saveexec_b64 s[14:15], s[12:13]
	v_mov_b32_e32 v16, 1
	s_or_b64 exec, exec, s[14:15]
